# attnA second-pass epilogue de-serialised: sub-norm gain quads loaded up front into dead registers, 16 result stores no longer each wait on the previous store
# baseline (speedup 1.0000x reference)
.LBB0_1350:
	global_load_dwordx4 v[132:135], v[178:179], off offset:32
	global_load_dwordx4 v[136:139], v[178:179], off offset:64
	global_load_dwordx4 v[140:143], v[178:179], off offset:96
	global_load_dwordx4 v[144:147], v[178:179], off offset:128
	global_load_dwordx4 v[148:151], v[178:179], off offset:160
	global_load_dwordx4 v[152:155], v[178:179], off offset:192
	global_load_dwordx4 v[156:159], v[178:179], off offset:224
	global_load_dwordx4 v[160:163], v[178:179], off offset:256
	global_load_dwordx4 v[164:167], v[178:179], off offset:288
	global_load_dwordx4 v[168:171], v[178:179], off offset:320
	global_load_dwordx4 v[172:175], v[178:179], off offset:352
	global_load_dwordx4 v[208:211], v[178:179], off offset:384
	global_load_dwordx4 v[216:219], v[178:179], off offset:416
	global_load_dwordx2 v[6:7], v[184:185], off offset:208
	global_load_dwordx2 v[8:9], v[184:185], off offset:224
	global_load_dwordx2 v[10:11], v[184:185], off offset:192
	global_load_dwordx2 v[12:13], v[184:185], off offset:240
	global_load_dwordx2 v[92:93], v[184:185], off
	global_load_dwordx2 v[100:101], v[184:185], off offset:16
	global_load_dwordx2 v[102:103], v[184:185], off offset:32
	global_load_dwordx2 v[104:105], v[184:185], off offset:48
	global_load_dwordx2 v[106:107], v[184:185], off offset:64
	global_load_dwordx2 v[108:109], v[184:185], off offset:80
	global_load_dwordx2 v[110:111], v[184:185], off offset:96
	global_load_dwordx2 v[128:129], v[184:185], off offset:112
	global_load_dwordx2 v[98:99], v[184:185], off offset:128
	global_load_dwordx2 v[90:91], v[184:185], off offset:144
	global_load_dwordx2 v[86:87], v[184:185], off offset:160
	global_load_dwordx2 v[84:85], v[184:185], off offset:176
	ds_bpermute_b32 v0, v192, v224
	v_mov_b32_e32 v14, v112
	v_mov_b32_e32 v15, v116
	v_mov_b32_e32 v116, v113
	v_mov_b32_e32 v81, v118
	s_waitcnt lgkmcnt(0)
	v_add_f32_e32 v0, v224, v0
	v_div_scale_f32 v94, s[2:3], v0, v0, 1.0
	v_rcp_f32_e32 v95, v94
	v_div_scale_f32 v96, vcc, 1.0, v0, 1.0
	v_mov_b32_e32 v118, v115
	v_fma_f32 v97, -v94, v95, 1.0
	v_fmac_f32_e32 v95, v97, v95
	v_mul_f32_e32 v97, v96, v95
	v_fma_f32 v112, -v94, v97, v96
	v_fmac_f32_e32 v97, v112, v95
	v_fma_f32 v94, -v94, v97, v96
	v_div_fmas_f32 v94, v94, v95, v97
	v_div_fixup_f32 v0, v94, v0, 1.0
	v_mov_b32_e32 v82, v120
	v_mov_b32_e32 v83, v124
	v_mov_b32_e32 v124, v121
	v_mov_b32_e32 v88, v122
	v_mov_b32_e32 v89, v126
	v_mov_b32_e32 v126, v123
	v_pk_mul_f32 v[14:15], v[14:15], v[0:1] op_sel_hi:[1,0]
	v_pk_mul_f32 v[94:95], v[116:117], v[0:1] op_sel_hi:[1,0]
	v_pk_mul_f32 v[96:97], v[118:119], v[0:1] op_sel_hi:[1,0]
	v_pk_mul_f32 v[118:119], v[66:67], v[0:1] op_sel_hi:[1,0]
	v_mov_b32_e32 v80, v114
	v_pk_mul_f32 v[112:113], v[82:83], v[0:1] op_sel_hi:[1,0]
	v_pk_mul_f32 v[88:89], v[88:89], v[0:1] op_sel_hi:[1,0]
	v_pk_mul_f32 v[116:117], v[126:127], v[0:1] op_sel_hi:[1,0]
	v_pk_mul_f32 v[80:81], v[80:81], v[0:1] op_sel_hi:[1,0]
	v_pk_mul_f32 v[114:115], v[124:125], v[0:1] op_sel_hi:[1,0]
	global_load_dwordx4 v[2:5], v[178:179], off
	v_pk_mul_f32 v[64:65], v[64:65], v[0:1] op_sel_hi:[1,0]
	v_pk_mul_f32 v[68:69], v[68:69], v[0:1] op_sel_hi:[1,0]
	v_pk_mul_f32 v[72:73], v[72:73], v[0:1] op_sel_hi:[1,0]
	v_pk_mul_f32 v[76:77], v[76:77], v[0:1] op_sel_hi:[1,0]
	v_pk_mul_f32 v[50:51], v[50:51], v[0:1] op_sel_hi:[1,0]
	v_pk_mul_f32 v[48:49], v[48:49], v[0:1] op_sel_hi:[1,0]
	v_pk_mul_f32 v[52:53], v[52:53], v[0:1] op_sel_hi:[1,0]
	v_pk_mul_f32 v[34:35], v[34:35], v[0:1] op_sel_hi:[1,0]
	v_pk_mul_f32 v[32:33], v[32:33], v[0:1] op_sel_hi:[1,0]
	v_pk_mul_f32 v[38:39], v[38:39], v[0:1] op_sel_hi:[1,0]
	v_pk_mul_f32 v[36:37], v[36:37], v[0:1] op_sel_hi:[1,0]
	v_pk_mul_f32 v[42:43], v[42:43], v[0:1] op_sel_hi:[1,0]
	v_pk_mul_f32 v[46:47], v[46:47], v[0:1] op_sel_hi:[1,0]
	v_pk_mul_f32 v[40:41], v[40:41], v[0:1] op_sel_hi:[1,0]
	v_pk_mul_f32 v[44:45], v[44:45], v[0:1] op_sel_hi:[1,0]
	s_mov_b64 s[4:5], 0
	s_waitcnt vmcnt(16)
	v_lshlrev_b32_e32 v67, 16, v6
	v_and_b32_e32 v121, 0xffff0000, v6
	s_waitcnt vmcnt(14)
	v_lshlrev_b32_e32 v66, 16, v10
	v_and_b32_e32 v120, 0xffff0000, v10
	s_waitcnt vmcnt(13)
	v_lshlrev_b32_e32 v127, 16, v13
	v_lshlrev_b32_e32 v126, 16, v9
	v_pk_fma_f32 v[82:83], v[176:177], v[14:15], v[66:67] neg_lo:[1,0,0] neg_hi:[1,0,0]
	v_pk_fma_f32 v[66:67], v[176:177], v[94:95], v[120:121] neg_lo:[1,0,0] neg_hi:[1,0,0]
	v_lshlrev_b32_e32 v123, 16, v7
	v_lshlrev_b32_e32 v122, 16, v11
	v_and_b32_e32 v6, 0xffff0000, v11
	v_lshlrev_b32_e32 v11, 16, v12
	v_and_b32_e32 v125, 0xffff0000, v12
	v_and_b32_e32 v131, 0xffff0000, v13
	v_pk_fma_f32 v[12:13], v[176:177], v[88:89], v[126:127] neg_lo:[1,0,0] neg_hi:[1,0,0]
	v_pk_mul_f32 v[88:89], v[66:67], v[66:67]
	v_and_b32_e32 v7, 0xffff0000, v7
	v_and_b32_e32 v124, 0xffff0000, v8
	v_pk_fma_f32 v[80:81], v[176:177], v[80:81], v[122:123] neg_lo:[1,0,0] neg_hi:[1,0,0]
	v_pk_fma_f32 v[88:89], v[82:83], v[82:83], v[88:89]
	v_pk_fma_f32 v[14:15], v[176:177], v[96:97], v[6:7] neg_lo:[1,0,0] neg_hi:[1,0,0]
	v_pk_fma_f32 v[6:7], v[176:177], v[114:115], v[124:125] neg_lo:[1,0,0] neg_hi:[1,0,0]
	v_pk_fma_f32 v[88:89], v[80:81], v[80:81], v[88:89]
	s_waitcnt vmcnt(12)
	v_lshlrev_b32_e32 v114, 16, v92
	v_and_b32_e32 v115, 0xffff0000, v92
	v_pk_fma_f32 v[96:97], v[14:15], v[14:15], v[88:89]
	v_lshlrev_b32_e32 v88, 16, v93
	v_and_b32_e32 v89, 0xffff0000, v93
	v_pk_fma_f32 v[92:93], v[176:177], v[64:65], v[114:115] neg_lo:[1,0,0] neg_hi:[1,0,0]
	v_pk_mul_f32 v[64:65], v[70:71], v[0:1] op_sel_hi:[1,0]
	s_waitcnt vmcnt(11)
	v_lshlrev_b32_e32 v70, 16, v101
	v_and_b32_e32 v71, 0xffff0000, v101
	v_pk_fma_f32 v[64:65], v[176:177], v[64:65], v[70:71] neg_lo:[1,0,0] neg_hi:[1,0,0]
	v_lshlrev_b32_e32 v70, 16, v100
	v_and_b32_e32 v71, 0xffff0000, v100
	v_pk_fma_f32 v[70:71], v[176:177], v[68:69], v[70:71] neg_lo:[1,0,0] neg_hi:[1,0,0]
	v_pk_mul_f32 v[68:69], v[74:75], v[0:1] op_sel_hi:[1,0]
	s_waitcnt vmcnt(10)
	v_lshlrev_b32_e32 v74, 16, v103
	v_and_b32_e32 v75, 0xffff0000, v103
	v_pk_fma_f32 v[68:69], v[176:177], v[68:69], v[74:75] neg_lo:[1,0,0] neg_hi:[1,0,0]
	v_lshlrev_b32_e32 v74, 16, v102
	v_and_b32_e32 v75, 0xffff0000, v102
	v_pk_fma_f32 v[74:75], v[176:177], v[72:73], v[74:75] neg_lo:[1,0,0] neg_hi:[1,0,0]
	v_pk_mul_f32 v[72:73], v[78:79], v[0:1] op_sel_hi:[1,0]
	s_waitcnt vmcnt(9)
	v_lshlrev_b32_e32 v78, 16, v105
	v_and_b32_e32 v79, 0xffff0000, v105
	v_pk_fma_f32 v[72:73], v[176:177], v[72:73], v[78:79] neg_lo:[1,0,0] neg_hi:[1,0,0]
	v_lshlrev_b32_e32 v78, 16, v104
	v_and_b32_e32 v79, 0xffff0000, v104
	v_pk_fma_f32 v[76:77], v[176:177], v[76:77], v[78:79] neg_lo:[1,0,0] neg_hi:[1,0,0]
	s_waitcnt vmcnt(8)
	v_lshlrev_b32_e32 v78, 16, v107
	v_and_b32_e32 v79, 0xffff0000, v107
	v_pk_fma_f32 v[50:51], v[176:177], v[50:51], v[78:79] neg_lo:[1,0,0] neg_hi:[1,0,0]
	v_lshlrev_b32_e32 v78, 16, v106
	v_and_b32_e32 v79, 0xffff0000, v106
	v_pk_fma_f32 v[78:79], v[176:177], v[48:49], v[78:79] neg_lo:[1,0,0] neg_hi:[1,0,0]
	v_pk_mul_f32 v[48:49], v[54:55], v[0:1] op_sel_hi:[1,0]
	s_waitcnt vmcnt(7)
	v_lshlrev_b32_e32 v54, 16, v109
	v_and_b32_e32 v55, 0xffff0000, v109
	v_pk_fma_f32 v[48:49], v[176:177], v[48:49], v[54:55] neg_lo:[1,0,0] neg_hi:[1,0,0]
	v_lshlrev_b32_e32 v54, 16, v108
	v_and_b32_e32 v55, 0xffff0000, v108
	v_pk_fma_f32 v[100:101], v[176:177], v[52:53], v[54:55] neg_lo:[1,0,0] neg_hi:[1,0,0]
	v_pk_mul_f32 v[52:53], v[58:59], v[0:1] op_sel_hi:[1,0]
	s_waitcnt vmcnt(6)
	v_lshlrev_b32_e32 v54, 16, v111
	v_and_b32_e32 v55, 0xffff0000, v111
	v_pk_fma_f32 v[52:53], v[176:177], v[52:53], v[54:55] neg_lo:[1,0,0] neg_hi:[1,0,0]
	v_pk_mul_f32 v[54:55], v[56:57], v[0:1] op_sel_hi:[1,0]
	v_lshlrev_b32_e32 v56, 16, v110
	v_and_b32_e32 v57, 0xffff0000, v110
	v_pk_fma_f32 v[56:57], v[176:177], v[54:55], v[56:57] neg_lo:[1,0,0] neg_hi:[1,0,0]
	v_pk_mul_f32 v[54:55], v[62:63], v[0:1] op_sel_hi:[1,0]
	s_waitcnt vmcnt(5)
	v_lshlrev_b32_e32 v58, 16, v129
	v_and_b32_e32 v59, 0xffff0000, v129
	v_pk_fma_f32 v[54:55], v[176:177], v[54:55], v[58:59] neg_lo:[1,0,0] neg_hi:[1,0,0]
	v_pk_mul_f32 v[58:59], v[60:61], v[0:1] op_sel_hi:[1,0]
	v_lshlrev_b32_e32 v60, 16, v128
	v_and_b32_e32 v61, 0xffff0000, v128
	v_pk_fma_f32 v[58:59], v[176:177], v[58:59], v[60:61] neg_lo:[1,0,0] neg_hi:[1,0,0]
	v_mov_b32_e32 v128, v57
	v_mov_b32_e32 v129, v59
	v_mov_b32_e32 v110, v56
	v_mov_b32_e32 v111, v58
	v_pk_mul_f32 v[128:129], v[128:129], v[128:129]
	v_mov_b32_e32 v60, v52
	v_mov_b32_e32 v61, v54
	v_pk_fma_f32 v[110:111], v[110:111], v[110:111], v[128:129]
	v_mov_b32_e32 v62, v53
	v_mov_b32_e32 v63, v55
	v_pk_fma_f32 v[60:61], v[60:61], v[60:61], v[110:111]
	v_lshlrev_b32_e32 v10, 16, v8
	v_pk_fma_f32 v[60:61], v[62:63], v[62:63], v[60:61]
	s_waitcnt vmcnt(4)
	v_lshlrev_b32_e32 v62, 16, v99
	v_and_b32_e32 v63, 0xffff0000, v99
	v_pk_fma_f32 v[34:35], v[176:177], v[34:35], v[62:63] neg_lo:[1,0,0] neg_hi:[1,0,0]
	v_lshlrev_b32_e32 v62, 16, v98
	v_and_b32_e32 v63, 0xffff0000, v98
	v_pk_fma_f32 v[32:33], v[176:177], v[32:33], v[62:63] neg_lo:[1,0,0] neg_hi:[1,0,0]
	s_waitcnt vmcnt(3)
	v_lshlrev_b32_e32 v62, 16, v91
	v_and_b32_e32 v63, 0xffff0000, v91
	v_pk_fma_f32 v[38:39], v[176:177], v[38:39], v[62:63] neg_lo:[1,0,0] neg_hi:[1,0,0]
	v_lshlrev_b32_e32 v62, 16, v90
	v_and_b32_e32 v63, 0xffff0000, v90
	v_pk_fma_f32 v[36:37], v[176:177], v[36:37], v[62:63] neg_lo:[1,0,0] neg_hi:[1,0,0]
	v_mov_b32_e32 v110, v33
	v_mov_b32_e32 v111, v37
	v_mov_b32_e32 v98, v32
	v_mov_b32_e32 v99, v36
	v_pk_mul_f32 v[110:111], v[110:111], v[110:111]
	v_mov_b32_e32 v62, v34
	v_mov_b32_e32 v63, v38
	v_pk_fma_f32 v[98:99], v[98:99], v[98:99], v[110:111]
	v_mov_b32_e32 v90, v35
	v_mov_b32_e32 v91, v39
	v_pk_fma_f32 v[62:63], v[62:63], v[62:63], v[98:99]
	v_and_b32_e32 v130, 0xffff0000, v9
	v_pk_fma_f32 v[62:63], v[90:91], v[90:91], v[62:63]
	s_waitcnt vmcnt(2)
	v_lshlrev_b32_e32 v90, 16, v87
	v_and_b32_e32 v91, 0xffff0000, v87
	v_pk_fma_f32 v[42:43], v[176:177], v[42:43], v[90:91] neg_lo:[1,0,0] neg_hi:[1,0,0]
	v_lshlrev_b32_e32 v90, 16, v86
	v_and_b32_e32 v91, 0xffff0000, v86
	s_waitcnt vmcnt(1)
	v_lshlrev_b32_e32 v86, 16, v85
	v_and_b32_e32 v87, 0xffff0000, v85
	v_pk_fma_f32 v[46:47], v[176:177], v[46:47], v[86:87] neg_lo:[1,0,0] neg_hi:[1,0,0]
	v_lshlrev_b32_e32 v86, 16, v84
	v_and_b32_e32 v87, 0xffff0000, v84
	v_pk_fma_f32 v[40:41], v[176:177], v[40:41], v[90:91] neg_lo:[1,0,0] neg_hi:[1,0,0]
	v_pk_fma_f32 v[44:45], v[176:177], v[44:45], v[86:87] neg_lo:[1,0,0] neg_hi:[1,0,0]
	v_mov_b32_e32 v98, v41
	v_mov_b32_e32 v99, v45
	v_mov_b32_e32 v90, v40
	v_mov_b32_e32 v91, v44
	v_pk_mul_f32 v[98:99], v[98:99], v[98:99]
	v_mov_b32_e32 v84, v42
	v_mov_b32_e32 v85, v46
	v_pk_fma_f32 v[90:91], v[90:91], v[90:91], v[98:99]
	v_pk_fma_f32 v[88:89], v[176:177], v[118:119], v[88:89] neg_lo:[1,0,0] neg_hi:[1,0,0]
	v_pk_mul_f32 v[114:115], v[92:93], v[92:93]
	v_pk_mul_f32 v[118:119], v[70:71], v[70:71]
	v_mov_b32_e32 v86, v43
	v_mov_b32_e32 v87, v47
	v_pk_fma_f32 v[84:85], v[84:85], v[84:85], v[90:91]
	v_pk_fma_f32 v[8:9], v[176:177], v[112:113], v[10:11] neg_lo:[1,0,0] neg_hi:[1,0,0]
	v_pk_fma_f32 v[10:11], v[176:177], v[116:117], v[130:131] neg_lo:[1,0,0] neg_hi:[1,0,0]
	v_pk_mul_f32 v[112:113], v[88:89], v[88:89]
	v_pk_mul_f32 v[116:117], v[64:65], v[64:65]
	v_pk_fma_f32 v[84:85], v[86:87], v[86:87], v[84:85]
	v_add_f32_e32 v0, v118, v119
	v_add_f32_e32 v86, v114, v115
	v_add_f32_e32 v0, v116, v0
	v_add_f32_e32 v86, v112, v86
	v_pk_mul_f32 v[102:103], v[74:75], v[74:75]
	v_add_f32_e32 v0, v117, v0
	v_add_f32_e32 v86, v113, v86
	v_pk_mul_f32 v[120:121], v[68:69], v[68:69]
	v_add_f32_e32 v0, v86, v0
	v_add_f32_e32 v86, v102, v103
	v_add_f32_e32 v86, v120, v86
	v_pk_mul_f32 v[104:105], v[76:77], v[76:77]
	v_add_f32_e32 v86, v121, v86
	v_pk_mul_f32 v[122:123], v[72:73], v[72:73]
	v_add_f32_e32 v0, v0, v86
	v_add_f32_e32 v86, v104, v105
	v_add_f32_e32 v86, v122, v86
	v_pk_mul_f32 v[106:107], v[78:79], v[78:79]
	v_add_f32_e32 v86, v123, v86
	v_pk_mul_f32 v[124:125], v[50:51], v[50:51]
	v_add_f32_e32 v0, v0, v86
	v_add_f32_e32 v86, v106, v107
	v_add_f32_e32 v86, v124, v86
	v_pk_mul_f32 v[108:109], v[100:101], v[100:101]
	v_add_f32_e32 v86, v125, v86
	v_pk_mul_f32 v[126:127], v[48:49], v[48:49]
	v_add_f32_e32 v0, v0, v86
	v_add_f32_e32 v86, v108, v109
	v_add_f32_e32 v86, v126, v86
	v_add_f32_e32 v86, v127, v86
	v_add_f32_e32 v0, v0, v86
	v_add_f32_e32 v0, v0, v60
	v_add_f32_e32 v0, v0, v61
	v_add_f32_e32 v0, v0, v62
	v_add_f32_e32 v0, v0, v63
	v_pk_mul_f32 v[94:95], v[6:7], v[6:7]
	v_add_f32_e32 v0, v0, v84
	v_pk_fma_f32 v[94:95], v[8:9], v[8:9], v[94:95]
	v_add_f32_e32 v0, v0, v85
	v_pk_fma_f32 v[94:95], v[12:13], v[12:13], v[94:95]
	v_add_f32_e32 v0, v0, v96
	v_pk_fma_f32 v[94:95], v[10:11], v[10:11], v[94:95]
	v_add_f32_e32 v0, v0, v97
	v_add_f32_e32 v0, v0, v94
	v_add_f32_e32 v0, v0, v95
	ds_bpermute_b32 v60, v192, v0
	s_waitcnt lgkmcnt(0)
	v_add_f32_e32 v0, v0, v60
	v_fmamk_f32 v0, v0, 0x3c000000, v206
	v_mul_f32_e32 v60, 0x4b800000, v0
	v_cmp_gt_f32_e32 vcc, s58, v0
	s_nop 1
	v_cndmask_b32_e32 v0, v0, v60, vcc
	v_rsq_f32_e32 v0, v0
	s_nop 0
	v_mul_f32_e32 v60, 0x45800000, v0
	v_cndmask_b32_e32 v0, v0, v60, vcc
	v_mul_f32_e32 v0, v193, v0
	v_pk_mul_f32 v[60:61], v[92:93], v[0:1] op_sel_hi:[1,0]
	v_pk_mul_f32 v[62:63], v[72:73], v[0:1] op_sel_hi:[1,0]
	s_waitcnt vmcnt(0)
	v_pk_mul_f32 v[2:3], v[2:3], v[60:61]
	v_pk_mul_f32 v[60:61], v[88:89], v[0:1] op_sel_hi:[1,0]
	v_cvt_pk_bf16_f32 v2, v2, v3
	v_pk_mul_f32 v[4:5], v[4:5], v[60:61]
	v_pk_mul_f32 v[60:61], v[70:71], v[0:1] op_sel_hi:[1,0]
	v_cvt_pk_bf16_f32 v3, v4, v5
	global_store_dwordx2 v[184:185], v[2:3], off
	v_pk_mul_f32 v[50:51], v[50:51], v[0:1] op_sel_hi:[1,0]
	v_pk_mul_f32 v[48:49], v[48:49], v[0:1] op_sel_hi:[1,0]
	v_pk_mul_f32 v[32:33], v[32:33], v[0:1] op_sel_hi:[1,0]
	v_pk_mul_f32 v[34:35], v[34:35], v[0:1] op_sel_hi:[1,0]
	s_and_b64 vcc, exec, s[14:15]
	v_pk_mul_f32 v[2:3], v[132:133], v[60:61]
	v_pk_mul_f32 v[60:61], v[64:65], v[0:1] op_sel_hi:[1,0]
	v_cvt_pk_bf16_f32 v2, v2, v3
	v_pk_mul_f32 v[4:5], v[134:135], v[60:61]
	v_pk_mul_f32 v[60:61], v[74:75], v[0:1] op_sel_hi:[1,0]
	v_cvt_pk_bf16_f32 v3, v4, v5
	global_store_dwordx2 v[184:185], v[2:3], off offset:16
	global_load_dwordx4 v[132:135], v[178:179], off offset:448
	v_pk_mul_f32 v[2:3], v[136:137], v[60:61]
	v_pk_mul_f32 v[60:61], v[68:69], v[0:1] op_sel_hi:[1,0]
	v_cvt_pk_bf16_f32 v2, v2, v3
	v_pk_mul_f32 v[4:5], v[138:139], v[60:61]
	v_pk_mul_f32 v[60:61], v[76:77], v[0:1] op_sel_hi:[1,0]
	v_cvt_pk_bf16_f32 v3, v4, v5
	global_store_dwordx2 v[184:185], v[2:3], off offset:32
	global_load_dwordx4 v[136:139], v[178:179], off offset:480
	v_pk_mul_f32 v[2:3], v[140:141], v[60:61]
	v_pk_mul_f32 v[4:5], v[142:143], v[62:63]
	v_cvt_pk_bf16_f32 v2, v2, v3
	v_cvt_pk_bf16_f32 v3, v4, v5
	global_store_dwordx2 v[184:185], v[2:3], off offset:48
	v_pk_mul_f32 v[60:61], v[78:79], v[0:1] op_sel_hi:[1,0]
	v_pk_mul_f32 v[4:5], v[146:147], v[50:51]
	v_pk_mul_f32 v[2:3], v[144:145], v[60:61]
	v_pk_mul_f32 v[50:51], v[100:101], v[0:1] op_sel_hi:[1,0]
	v_cvt_pk_bf16_f32 v2, v2, v3
	v_cvt_pk_bf16_f32 v3, v4, v5
	global_store_dwordx2 v[184:185], v[2:3], off offset:64
	v_pk_mul_f32 v[2:3], v[148:149], v[50:51]
	v_pk_mul_f32 v[4:5], v[150:151], v[48:49]
	v_cvt_pk_bf16_f32 v2, v2, v3
	v_cvt_pk_bf16_f32 v3, v4, v5
	global_store_dwordx2 v[184:185], v[2:3], off offset:80
	v_pk_mul_f32 v[48:49], v[56:57], v[0:1] op_sel_hi:[1,0]
	v_pk_mul_f32 v[50:51], v[52:53], v[0:1] op_sel_hi:[1,0]
	v_pk_mul_f32 v[2:3], v[152:153], v[48:49]
	v_pk_mul_f32 v[4:5], v[154:155], v[50:51]
	v_cvt_pk_bf16_f32 v2, v2, v3
	v_cvt_pk_bf16_f32 v3, v4, v5
	global_store_dwordx2 v[184:185], v[2:3], off offset:96
	v_pk_mul_f32 v[48:49], v[58:59], v[0:1] op_sel_hi:[1,0]
	v_pk_mul_f32 v[50:51], v[54:55], v[0:1] op_sel_hi:[1,0]
	v_pk_mul_f32 v[2:3], v[156:157], v[48:49]
	v_pk_mul_f32 v[4:5], v[158:159], v[50:51]
	v_cvt_pk_bf16_f32 v2, v2, v3
	v_cvt_pk_bf16_f32 v3, v4, v5
	global_store_dwordx2 v[184:185], v[2:3], off offset:112
	v_pk_mul_f32 v[2:3], v[160:161], v[32:33]
	v_pk_mul_f32 v[4:5], v[162:163], v[34:35]
	v_cvt_pk_bf16_f32 v2, v2, v3
	v_cvt_pk_bf16_f32 v3, v4, v5
	global_store_dwordx2 v[184:185], v[2:3], off offset:128
	v_pk_mul_f32 v[32:33], v[36:37], v[0:1] op_sel_hi:[1,0]
	v_pk_mul_f32 v[34:35], v[38:39], v[0:1] op_sel_hi:[1,0]
	v_pk_mul_f32 v[2:3], v[32:33], v[164:165]
	v_pk_mul_f32 v[4:5], v[34:35], v[166:167]
	v_cvt_pk_bf16_f32 v2, v2, v3
	v_cvt_pk_bf16_f32 v3, v4, v5
	global_store_dwordx2 v[184:185], v[2:3], off offset:144
	v_pk_mul_f32 v[32:33], v[40:41], v[0:1] op_sel_hi:[1,0]
	v_pk_mul_f32 v[34:35], v[42:43], v[0:1] op_sel_hi:[1,0]
	v_pk_mul_f32 v[2:3], v[32:33], v[168:169]
	v_pk_mul_f32 v[4:5], v[34:35], v[170:171]
	v_cvt_pk_bf16_f32 v2, v2, v3
	v_cvt_pk_bf16_f32 v3, v4, v5
	global_store_dwordx2 v[184:185], v[2:3], off offset:160
	v_pk_mul_f32 v[32:33], v[44:45], v[0:1] op_sel_hi:[1,0]
	v_pk_mul_f32 v[34:35], v[46:47], v[0:1] op_sel_hi:[1,0]
	v_pk_mul_f32 v[2:3], v[32:33], v[172:173]
	v_pk_mul_f32 v[4:5], v[34:35], v[174:175]
	v_cvt_pk_bf16_f32 v2, v2, v3
	v_cvt_pk_bf16_f32 v3, v4, v5
	global_store_dwordx2 v[184:185], v[2:3], off offset:176
	v_mov_b32_e32 v32, v82
	v_mov_b32_e32 v33, v66
	v_mov_b32_e32 v34, v80
	v_mov_b32_e32 v35, v14
	v_pk_mul_f32 v[32:33], v[32:33], v[0:1] op_sel_hi:[1,0]
	v_pk_mul_f32 v[34:35], v[34:35], v[0:1] op_sel_hi:[1,0]
	v_mov_b32_e32 v66, v83
	v_mov_b32_e32 v14, v81
	v_pk_mul_f32 v[14:15], v[14:15], v[0:1] op_sel_hi:[1,0]
	v_pk_mul_f32 v[2:3], v[32:33], v[208:209]
	v_pk_mul_f32 v[4:5], v[34:35], v[210:211]
	v_cvt_pk_bf16_f32 v2, v2, v3
	v_cvt_pk_bf16_f32 v3, v4, v5
	global_store_dwordx2 v[184:185], v[2:3], off offset:192
	v_pk_mul_f32 v[32:33], v[66:67], v[0:1] op_sel_hi:[1,0]
	v_pk_mul_f32 v[4:5], v[14:15], v[218:219]
	v_pk_mul_f32 v[2:3], v[32:33], v[216:217]
	v_mov_b32_e32 v14, v8
	v_cvt_pk_bf16_f32 v2, v2, v3
	v_cvt_pk_bf16_f32 v3, v4, v5
	global_store_dwordx2 v[184:185], v[2:3], off offset:208
	v_mov_b32_e32 v15, v6
	v_mov_b32_e32 v32, v12
	v_mov_b32_e32 v33, v10
	v_pk_mul_f32 v[14:15], v[14:15], v[0:1] op_sel_hi:[1,0]
	v_pk_mul_f32 v[32:33], v[32:33], v[0:1] op_sel_hi:[1,0]
	v_mov_b32_e32 v6, v9
	v_mov_b32_e32 v10, v13
	v_pk_mul_f32 v[6:7], v[6:7], v[0:1] op_sel_hi:[1,0]
	v_pk_mul_f32 v[8:9], v[10:11], v[0:1] op_sel_hi:[1,0]
	s_waitcnt vmcnt(13)
	v_pk_mul_f32 v[2:3], v[14:15], v[132:133]
	v_pk_mul_f32 v[4:5], v[32:33], v[134:135]
	v_cvt_pk_bf16_f32 v2, v2, v3
	v_cvt_pk_bf16_f32 v3, v4, v5
	global_store_dwordx2 v[184:185], v[2:3], off offset:224
	s_waitcnt vmcnt(12)
	v_pk_mul_f32 v[2:3], v[6:7], v[136:137]
	v_pk_mul_f32 v[4:5], v[8:9], v[138:139]
	v_cvt_pk_bf16_f32 v2, v2, v3
	v_cvt_pk_bf16_f32 v3, v4, v5
	global_store_dwordx2 v[184:185], v[2:3], off offset:240
	s_cbranch_vccnz .LBB0_1348
